# w_out/w_ff1/w_ff2 bf16 transposes moved from P0 into idle workgroups of the scan phase (nt loads/stores); 2 prefetch helpers per chain
# baseline (speedup 1.0000x reference)
_Z14fwd_megakernel4Args:
	s_load_dwordx8 s[52:59], s[0:1], 0x80
	s_load_dword s3, s[0:1], 0xa0
	s_add_u32 s4, s0, 0x98
	v_and_b32_e32 v1, 0x3ff, v0
	s_addc_u32 s5, s1, 0
	v_readfirstlane_b32 s85, v1
	s_cmp_lt_u32 s85, 64
	s_cselect_b64 s[6:7], -1, 0
	s_cmp_gt_u32 s85, 63
	s_waitcnt lgkmcnt(0)
	v_writelane_b32 v240, s3, 0
	v_writelane_b32 v240, s0, 4
	v_writelane_b32 v240, s1, 5
	s_cbranch_scc1 .LBB0_4
	v_mbcnt_lo_u32_b32 v2, -1, 0
	v_mbcnt_hi_u32_b32 v2, -1, v2
	v_cmp_gt_i32_e32 vcc, 2, v2
	s_and_saveexec_b64 s[8:9], vcc
	v_lshl_add_u32 v2, v2, 2, 0
	v_add_u32_e32 v2, 0x23f00, v2
	v_mov_b32_e32 v3, 0
	ds_write_b32 v2, v3
	s_or_b64 exec, exec, s[8:9]

.LBB0_21:
	s_movk_i32 s101, 0x100
	s_lshr_b32 s95, s85, 6
	s_cmp_gt_u32 s2, 63
	s_cbranch_scc1 .Lpf_noinit
	s_cmp_lg_u32 s85, 0
	s_cbranch_scc1 .Lpf_noinit
	s_add_u32 s98, s54, 0x1ec04000
	s_addc_u32 s99, s55, 0
	s_lshl_b32 s100, s2, 8
	s_add_u32 s98, s98, s100
	s_addc_u32 s99, s99, 0
	v_mov_b32_e32 v239, 0
	global_store_dword v239, v239, s[98:99] sc0 sc1

.LBB0_40:
	s_abs_i32 s0, s58
	v_cvt_f32_u32_e32 v0, s0
	s_sub_i32 s4, 0, s0
	s_add_i32 s1, s2, 64
	s_ashr_i32 s3, s1, 31
	v_rcp_iflag_f32_e32 v0, v0
	s_abs_i32 s1, s1
	v_mul_f32_e32 v0, 0x4f7ffffe, v0
	v_cvt_u32_f32_e32 v0, v0
	s_nop 0
	v_readfirstlane_b32 s5, v0
	s_mul_i32 s4, s4, s5
	s_mul_hi_u32 s4, s5, s4
	s_add_i32 s5, s5, s4
	s_mul_hi_u32 s4, s1, s5
	s_mul_i32 s4, s4, s0
	s_sub_i32 s1, s1, s4
	s_sub_i32 s4, s1, s0
	s_cmp_ge_u32 s1, s0
	s_cselect_b32 s1, s4, s1
	s_sub_i32 s4, s1, s0
	s_cmp_ge_u32 s1, s0
	s_cselect_b32 s0, s4, s1
	s_xor_b32 s0, s0, s3
	s_sub_i32 s3, s0, s3
	s_cmp_ge_i32 s3, s101
	s_mov_b32 s1, 0
	s_cbranch_scc1 .LBB0_55
.Lp0_jobs_entry:
	v_lshlrev_b32_e32 v0, 4, v128
	v_and_b32_e32 v8, 0x3f0, v0
	v_lshlrev_b32_e32 v0, 3, v128
	v_ashrrev_i32_e32 v17, 3, v146
	v_and_b32_e32 v10, 56, v0
	v_mul_u32_u24_e32 v0, 0x404, v10
	v_lshlrev_b32_e32 v1, 2, v17
	v_mov_b32_e32 v9, 0
	v_add_u32_e32 v22, 0, v8
	v_add3_u32 v18, 0, v0, v1
	s_waitcnt lgkmcnt(0)
	v_lshl_add_u64 v[0:1], s[28:29], 0, v[8:9]
	v_lshl_add_u64 v[2:3], s[26:27], 0, v[8:9]
	v_lshl_add_u64 v[4:5], s[22:23], 0, v[8:9]
	v_lshl_add_u64 v[6:7], s[46:47], 0, v[8:9]
	v_lshlrev_b32_e32 v8, 1, v10
	v_ashrrev_i32_e32 v16, 6, v146
	s_movk_i32 s0, 0x404
	v_lshl_add_u64 v[8:9], s[54:55], 0, v[8:9]
	s_mov_b64 s[4:5], 0x1200000
	v_mul_lo_u32 v23, v16, s0
	v_lshl_add_u64 v[10:11], v[8:9], 0, s[4:5]
	s_mov_b64 s[4:5], 0xa00000
	v_lshl_add_u64 v[12:13], v[8:9], 0, s[4:5]
	s_mov_b64 s[4:5], 0x800000
	v_add_u32_e32 v22, v22, v23
	v_add_u32_e32 v19, 64, v17
	v_add_u32_e32 v20, 0x80, v17
	v_add_u32_e32 v21, 0xc0, v17
	v_lshl_add_u64 v[14:15], v[8:9], 0, s[4:5]
	s_lshl_b32 s12, s3, 8
	s_lshl_b32 s13, s58, 8
	s_lshl_b32 s14, s3, 4
	s_lshl_b32 s15, s58, 4
	s_lshl_b32 s22, s3, 2
	s_lshl_b32 s23, s58, 2
	v_add_u32_e32 v23, 0x2020, v22
	v_add_u32_e32 v24, 0x2028, v22
	v_add_u32_e32 v25, 0x4040, v22
	v_add_u32_e32 v26, 0x4048, v22
	v_add_u32_e32 v27, 0x6060, v22
	v_add_u32_e32 v28, 0x6068, v22
	v_add_u32_e32 v29, 0x8080, v22
	v_add_u32_e32 v30, 0x8088, v22
	v_add_u32_e32 v31, 0xa0a0, v22
	v_add_u32_e32 v32, 0xa0a8, v22
	v_add_u32_e32 v33, 0xc0c0, v22
	v_add_u32_e32 v34, 0xc0c8, v22
	v_add_u32_e32 v35, 0xe0e0, v22
	v_add_u32_e32 v36, 0xe0e8, v22
	s_movk_i32 s28, 0x4020
	v_add_u32_e32 v37, 4, v18
	v_add_u32_e32 v38, 8, v18
	v_add_u32_e32 v39, 12, v18
	v_add_u32_e32 v40, 16, v18
	v_add_u32_e32 v41, 20, v18
	v_add_u32_e32 v42, 24, v18
	v_add_u32_e32 v43, 28, v18
	s_branch .LBB0_43
.LBB0_42:
	s_add_i32 s3, s3, s58
	s_add_i32 s12, s12, s13
	s_add_i32 s14, s14, s15
	s_add_i32 s22, s22, s23
	s_cmp_lt_i32 s3, s101
	s_cbranch_scc0 .LBB0_55
.LBB0_43:
	s_cmpk_gt_i32 s3, 0xff
	s_mov_b64 s[4:5], -1
	s_cbranch_scc0 .LBB0_53
	s_cmpk_gt_u32 s3, 0x13f
	s_cbranch_scc0 .LBB0_50
	s_cmpk_gt_u32 s3, 0x23f
	s_cbranch_scc0 .LBB0_47
	s_and_b32 s0, s14, 0x7fffffc0
	s_add_i32 s4, s0, 0xffffdc00
	s_and_b32 s29, s12, 0x300
	v_add_u32_e32 v44, s4, v16
	s_lshl_b32 s0, s29, 2
	v_ashrrev_i32_e32 v45, 31, v44
	v_lshl_add_u64 v[46:47], v[0:1], 0, s[0:1]
	v_lshlrev_b64 v[44:45], 12, v[44:45]
	v_lshl_add_u64 v[72:73], v[46:47], 0, v[44:45]
	v_add_co_u32_e32 v48, vcc, 0x8000, v72
	v_add_u32_e32 v76, s29, v17
	s_nop 0
	v_addc_co_u32_e32 v49, vcc, 0, v73, vcc
	v_add_co_u32_e32 v52, vcc, 0x10000, v72
	global_load_dwordx4 v[44:47], v[72:73], off nt
	s_nop 0
	global_load_dwordx4 v[48:51], v[48:49], off nt
	v_addc_co_u32_e32 v53, vcc, 0, v73, vcc
	v_add_co_u32_e32 v56, vcc, 0x18000, v72
	s_mov_b32 s5, s1
	s_nop 0
	v_addc_co_u32_e32 v57, vcc, 0, v73, vcc
	v_add_co_u32_e32 v60, vcc, 0x20000, v72
	global_load_dwordx4 v[52:55], v[52:53], off nt
	s_nop 0
	global_load_dwordx4 v[56:59], v[56:57], off nt
	v_addc_co_u32_e32 v61, vcc, 0, v73, vcc
	v_add_co_u32_e32 v64, vcc, 0x28000, v72
	v_ashrrev_i32_e32 v77, 31, v76
	s_nop 0
	v_addc_co_u32_e32 v65, vcc, 0, v73, vcc
	global_load_dwordx4 v[60:63], v[60:61], off nt
	s_nop 0
	global_load_dwordx4 v[64:67], v[64:65], off nt
	v_add_co_u32_e32 v68, vcc, 0x30000, v72
	v_lshl_add_u64 v[78:79], s[4:5], 1, v[10:11]
	s_nop 0
	v_addc_co_u32_e32 v69, vcc, 0, v73, vcc
	global_load_dwordx4 v[68:71], v[68:69], off nt
	v_add_co_u32_e32 v72, vcc, 0x38000, v72
	v_lshlrev_b64 v[76:77], 13, v[76:77]
	s_nop 0
	v_addc_co_u32_e32 v73, vcc, 0, v73, vcc
	global_load_dwordx4 v[72:75], v[72:73], off nt
	v_lshl_add_u64 v[76:77], v[78:79], 0, v[76:77]
	s_mov_b64 s[4:5], 0
	s_waitcnt vmcnt(7)
	ds_write2_b32 v22, v44, v45 offset1:1
	ds_write2_b32 v22, v46, v47 offset0:2 offset1:3
	s_waitcnt vmcnt(6)
	ds_write2_b32 v23, v48, v49 offset1:1
	ds_write2_b32 v24, v50, v51 offset1:1
	s_waitcnt vmcnt(5)
	ds_write2_b32 v25, v52, v53 offset1:1
	ds_write2_b32 v26, v54, v55 offset1:1
	s_waitcnt vmcnt(4)
	ds_write2_b32 v27, v56, v57 offset1:1
	ds_write2_b32 v28, v58, v59 offset1:1
	s_waitcnt vmcnt(3)
	ds_write2_b32 v29, v60, v61 offset1:1
	ds_write2_b32 v30, v62, v63 offset1:1
	s_waitcnt vmcnt(2)
	ds_write2_b32 v31, v64, v65 offset1:1
	ds_write2_b32 v32, v66, v67 offset1:1
	s_waitcnt vmcnt(1)
	ds_write2_b32 v33, v68, v69 offset1:1
	ds_write2_b32 v34, v70, v71 offset1:1
	s_waitcnt vmcnt(0)
	ds_write2_b32 v35, v72, v73 offset1:1
	ds_write2_b32 v36, v74, v75 offset1:1
	s_waitcnt lgkmcnt(0)
	s_barrier
	ds_read2st64_b32 v[48:49], v18 offset1:1
	ds_read2st64_b32 v[52:53], v18 offset0:2 offset1:3
	ds_read2st64_b32 v[50:51], v37 offset0:4 offset1:5
	ds_read2st64_b32 v[54:55], v37 offset0:6 offset1:7
	ds_read2st64_b32 v[56:57], v38 offset0:8 offset1:9
	ds_read2st64_b32 v[58:59], v38 offset0:10 offset1:11
	ds_read2st64_b32 v[60:61], v39 offset0:12 offset1:13
	ds_read2st64_b32 v[62:63], v39 offset0:14 offset1:15
	ds_read2st64_b32 v[64:65], v40 offset0:16 offset1:17
	ds_read2st64_b32 v[66:67], v40 offset0:18 offset1:19
	ds_read2st64_b32 v[68:69], v41 offset0:20 offset1:21
	ds_read2st64_b32 v[70:71], v41 offset0:22 offset1:23
	ds_read2st64_b32 v[72:73], v42 offset0:24 offset1:25
	ds_read2st64_b32 v[74:75], v42 offset0:26 offset1:27
	ds_read2st64_b32 v[80:81], v43 offset0:28 offset1:29
	ds_read2st64_b32 v[82:83], v43 offset0:30 offset1:31
	s_waitcnt lgkmcnt(13)
	v_cvt_pk_bf16_f32 v44, v48, v50
	s_waitcnt lgkmcnt(9)
	v_cvt_pk_bf16_f32 v45, v56, v60
	s_waitcnt lgkmcnt(5)
	v_cvt_pk_bf16_f32 v46, v64, v68
	s_waitcnt lgkmcnt(1)
	v_cvt_pk_bf16_f32 v47, v72, v80
	global_store_dwordx4 v[76:77], v[44:47], off nt
	v_cvt_pk_bf16_f32 v48, v49, v51
	v_cvt_pk_bf16_f32 v49, v57, v61
	v_add_u32_e32 v44, s29, v19
	v_ashrrev_i32_e32 v45, 31, v44
	v_lshlrev_b64 v[44:45], 13, v[44:45]
	v_cvt_pk_bf16_f32 v50, v65, v69
	v_cvt_pk_bf16_f32 v51, v73, v81
	v_lshl_add_u64 v[44:45], v[78:79], 0, v[44:45]
	global_store_dwordx4 v[44:45], v[48:51], off nt
	v_cvt_pk_bf16_f32 v44, v52, v54
	v_cvt_pk_bf16_f32 v45, v58, v62
	v_add_u32_e32 v48, s29, v20
	v_ashrrev_i32_e32 v49, 31, v48
	v_lshlrev_b64 v[48:49], 13, v[48:49]
	v_cvt_pk_bf16_f32 v46, v66, v70
	s_waitcnt lgkmcnt(0)
	v_cvt_pk_bf16_f32 v47, v74, v82
	v_lshl_add_u64 v[48:49], v[78:79], 0, v[48:49]
	global_store_dwordx4 v[48:49], v[44:47], off nt
	v_add_u32_e32 v48, s29, v21
	v_ashrrev_i32_e32 v49, 31, v48
	v_lshlrev_b64 v[48:49], 13, v[48:49]
	v_cvt_pk_bf16_f32 v44, v53, v55
	v_cvt_pk_bf16_f32 v45, v59, v63
	v_cvt_pk_bf16_f32 v46, v67, v71
	v_cvt_pk_bf16_f32 v47, v75, v83
	v_lshl_add_u64 v[48:49], v[78:79], 0, v[48:49]
	global_store_dwordx4 v[48:49], v[44:47], off nt
	s_barrier
.LBB0_47:
	s_andn2_b64 vcc, exec, s[4:5]
	s_cbranch_vccnz .LBB0_49
	s_and_b32 s0, s22, 0xfc0
	s_add_i32 s4, s0, 0xfffffb00
	s_and_b32 s29, s12, 0xf00
	v_add_u32_e32 v44, s4, v16
	s_lshl_b32 s0, s29, 2
	v_ashrrev_i32_e32 v45, 31, v44
	v_lshl_add_u64 v[46:47], v[2:3], 0, s[0:1]
	v_lshlrev_b64 v[44:45], 14, v[44:45]
	v_lshl_add_u64 v[72:73], v[46:47], 0, v[44:45]
	v_add_co_u32_e32 v48, vcc, 0x20000, v72
	v_add_u32_e32 v76, s29, v17
	s_nop 0
	v_addc_co_u32_e32 v49, vcc, 0, v73, vcc
	v_add_co_u32_e32 v52, vcc, 0x40000, v72
	global_load_dwordx4 v[44:47], v[72:73], off nt
	s_nop 0
	global_load_dwordx4 v[48:51], v[48:49], off nt
	v_addc_co_u32_e32 v53, vcc, 0, v73, vcc
	v_add_co_u32_e32 v56, vcc, 0x60000, v72
	s_mov_b32 s5, s1
	s_nop 0
	v_addc_co_u32_e32 v57, vcc, 0, v73, vcc
	v_add_co_u32_e32 v60, vcc, 0x80000, v72
	global_load_dwordx4 v[52:55], v[52:53], off nt
	s_nop 0
	global_load_dwordx4 v[56:59], v[56:57], off nt
	v_addc_co_u32_e32 v61, vcc, 0, v73, vcc
	v_add_co_u32_e32 v64, vcc, 0xa0000, v72
	v_ashrrev_i32_e32 v77, 31, v76
	s_nop 0
	v_addc_co_u32_e32 v65, vcc, 0, v73, vcc
	global_load_dwordx4 v[60:63], v[60:61], off nt
	s_nop 0
	global_load_dwordx4 v[64:67], v[64:65], off nt
	v_add_co_u32_e32 v68, vcc, 0xc0000, v72
	v_lshl_add_u64 v[78:79], s[4:5], 1, v[12:13]
	s_nop 0
	v_addc_co_u32_e32 v69, vcc, 0, v73, vcc
	global_load_dwordx4 v[68:71], v[68:69], off nt
	v_add_co_u32_e32 v72, vcc, 0xe0000, v72
	v_lshlrev_b64 v[76:77], 11, v[76:77]
	s_nop 0
	v_addc_co_u32_e32 v73, vcc, 0, v73, vcc
	global_load_dwordx4 v[72:75], v[72:73], off nt
	v_lshl_add_u64 v[76:77], v[78:79], 0, v[76:77]
	s_waitcnt vmcnt(7)
	ds_write2_b32 v22, v44, v45 offset1:1
	ds_write2_b32 v22, v46, v47 offset0:2 offset1:3
	s_waitcnt vmcnt(6)
	ds_write2_b32 v23, v48, v49 offset1:1
	ds_write2_b32 v24, v50, v51 offset1:1
	s_waitcnt vmcnt(5)
	ds_write2_b32 v25, v52, v53 offset1:1
	ds_write2_b32 v26, v54, v55 offset1:1
	s_waitcnt vmcnt(4)
	ds_write2_b32 v27, v56, v57 offset1:1
	ds_write2_b32 v28, v58, v59 offset1:1
	s_waitcnt vmcnt(3)
	ds_write2_b32 v29, v60, v61 offset1:1
	ds_write2_b32 v30, v62, v63 offset1:1
	s_waitcnt vmcnt(2)
	ds_write2_b32 v31, v64, v65 offset1:1
	ds_write2_b32 v32, v66, v67 offset1:1
	s_waitcnt vmcnt(1)
	ds_write2_b32 v33, v68, v69 offset1:1
	ds_write2_b32 v34, v70, v71 offset1:1
	s_waitcnt vmcnt(0)
	ds_write2_b32 v35, v72, v73 offset1:1
	ds_write2_b32 v36, v74, v75 offset1:1
	s_waitcnt lgkmcnt(0)
	s_barrier
	ds_read2st64_b32 v[48:49], v18 offset1:1
	ds_read2st64_b32 v[52:53], v18 offset0:2 offset1:3
	ds_read2st64_b32 v[50:51], v37 offset0:4 offset1:5
	ds_read2st64_b32 v[54:55], v37 offset0:6 offset1:7
	ds_read2st64_b32 v[56:57], v38 offset0:8 offset1:9
	ds_read2st64_b32 v[58:59], v38 offset0:10 offset1:11
	ds_read2st64_b32 v[60:61], v39 offset0:12 offset1:13
	ds_read2st64_b32 v[62:63], v39 offset0:14 offset1:15
	ds_read2st64_b32 v[64:65], v40 offset0:16 offset1:17
	ds_read2st64_b32 v[66:67], v40 offset0:18 offset1:19
	ds_read2st64_b32 v[68:69], v41 offset0:20 offset1:21
	ds_read2st64_b32 v[70:71], v41 offset0:22 offset1:23
	ds_read2st64_b32 v[72:73], v42 offset0:24 offset1:25
	ds_read2st64_b32 v[74:75], v42 offset0:26 offset1:27
	ds_read2st64_b32 v[80:81], v43 offset0:28 offset1:29
	ds_read2st64_b32 v[82:83], v43 offset0:30 offset1:31
	s_waitcnt lgkmcnt(13)
	v_cvt_pk_bf16_f32 v44, v48, v50
	s_waitcnt lgkmcnt(9)
	v_cvt_pk_bf16_f32 v45, v56, v60
	s_waitcnt lgkmcnt(5)
	v_cvt_pk_bf16_f32 v46, v64, v68
	s_waitcnt lgkmcnt(1)
	v_cvt_pk_bf16_f32 v47, v72, v80
	global_store_dwordx4 v[76:77], v[44:47], off nt
	v_cvt_pk_bf16_f32 v48, v49, v51
	v_cvt_pk_bf16_f32 v49, v57, v61
	v_add_u32_e32 v44, s29, v19
	v_ashrrev_i32_e32 v45, 31, v44
	v_lshlrev_b64 v[44:45], 11, v[44:45]
	v_cvt_pk_bf16_f32 v50, v65, v69
	v_cvt_pk_bf16_f32 v51, v73, v81
	v_lshl_add_u64 v[44:45], v[78:79], 0, v[44:45]
	global_store_dwordx4 v[44:45], v[48:51], off nt
	v_cvt_pk_bf16_f32 v44, v52, v54
	v_cvt_pk_bf16_f32 v45, v58, v62
	v_add_u32_e32 v48, s29, v20
	v_ashrrev_i32_e32 v49, 31, v48
	v_lshlrev_b64 v[48:49], 11, v[48:49]
	v_cvt_pk_bf16_f32 v46, v66, v70
	s_waitcnt lgkmcnt(0)
	v_cvt_pk_bf16_f32 v47, v74, v82
	v_lshl_add_u64 v[48:49], v[78:79], 0, v[48:49]
	global_store_dwordx4 v[48:49], v[44:47], off nt
	v_add_u32_e32 v48, s29, v21
	v_ashrrev_i32_e32 v49, 31, v48
	v_lshlrev_b64 v[48:49], 11, v[48:49]
	v_cvt_pk_bf16_f32 v44, v53, v55
	v_cvt_pk_bf16_f32 v45, v59, v63
	v_cvt_pk_bf16_f32 v46, v67, v71
	v_cvt_pk_bf16_f32 v47, v75, v83
	v_lshl_add_u64 v[48:49], v[78:79], 0, v[48:49]
	global_store_dwordx4 v[48:49], v[44:47], off nt
	s_barrier

.LBB0_50:
	s_andn2_b64 vcc, exec, s[4:5]
	s_cbranch_vccnz .LBB0_52
	s_and_b32 s0, s14, 0x1fc0
	s_add_i32 s4, s0, 0xfffff000
	s_and_b32 s29, s12, 0x300
	v_add_u32_e32 v44, s4, v16
	s_lshl_b32 s0, s29, 2
	v_ashrrev_i32_e32 v45, 31, v44
	v_lshl_add_u64 v[46:47], v[4:5], 0, s[0:1]
	v_lshlrev_b64 v[44:45], 12, v[44:45]
	v_lshl_add_u64 v[72:73], v[46:47], 0, v[44:45]
	v_add_co_u32_e32 v48, vcc, 0x8000, v72
	v_add_u32_e32 v76, s29, v17
	s_nop 0
	v_addc_co_u32_e32 v49, vcc, 0, v73, vcc
	v_add_co_u32_e32 v52, vcc, 0x10000, v72
	global_load_dwordx4 v[44:47], v[72:73], off nt
	s_nop 0
	global_load_dwordx4 v[48:51], v[48:49], off nt
	v_addc_co_u32_e32 v53, vcc, 0, v73, vcc
	v_add_co_u32_e32 v56, vcc, 0x18000, v72
	s_mov_b32 s5, s1
	s_nop 0
	v_addc_co_u32_e32 v57, vcc, 0, v73, vcc
	v_add_co_u32_e32 v60, vcc, 0x20000, v72
	global_load_dwordx4 v[52:55], v[52:53], off nt
	s_nop 0
	global_load_dwordx4 v[56:59], v[56:57], off nt
	v_addc_co_u32_e32 v61, vcc, 0, v73, vcc
	v_add_co_u32_e32 v64, vcc, 0x28000, v72
	v_ashrrev_i32_e32 v77, 31, v76
	s_nop 0
	v_addc_co_u32_e32 v65, vcc, 0, v73, vcc
	global_load_dwordx4 v[60:63], v[60:61], off nt
	s_nop 0
	global_load_dwordx4 v[64:67], v[64:65], off nt
	v_add_co_u32_e32 v68, vcc, 0x30000, v72
	v_lshl_add_u64 v[78:79], s[4:5], 1, v[14:15]
	s_nop 0
	v_addc_co_u32_e32 v69, vcc, 0, v73, vcc
	global_load_dwordx4 v[68:71], v[68:69], off nt
	v_add_co_u32_e32 v72, vcc, 0x38000, v72
	v_lshlrev_b64 v[76:77], 11, v[76:77]
	s_nop 0
	v_addc_co_u32_e32 v73, vcc, 0, v73, vcc
	global_load_dwordx4 v[72:75], v[72:73], off nt
	v_lshl_add_u64 v[76:77], v[78:79], 0, v[76:77]
	s_waitcnt vmcnt(7)
	ds_write2_b32 v22, v44, v45 offset1:1
	ds_write2_b32 v22, v46, v47 offset0:2 offset1:3
	s_waitcnt vmcnt(6)
	ds_write2_b32 v23, v48, v49 offset1:1
	ds_write2_b32 v24, v50, v51 offset1:1
	s_waitcnt vmcnt(5)
	ds_write2_b32 v25, v52, v53 offset1:1
	ds_write2_b32 v26, v54, v55 offset1:1
	s_waitcnt vmcnt(4)
	ds_write2_b32 v27, v56, v57 offset1:1
	ds_write2_b32 v28, v58, v59 offset1:1
	s_waitcnt vmcnt(3)
	ds_write2_b32 v29, v60, v61 offset1:1
	ds_write2_b32 v30, v62, v63 offset1:1
	s_waitcnt vmcnt(2)
	ds_write2_b32 v31, v64, v65 offset1:1
	ds_write2_b32 v32, v66, v67 offset1:1
	s_waitcnt vmcnt(1)
	ds_write2_b32 v33, v68, v69 offset1:1
	ds_write2_b32 v34, v70, v71 offset1:1
	s_waitcnt vmcnt(0)
	ds_write2_b32 v35, v72, v73 offset1:1
	ds_write2_b32 v36, v74, v75 offset1:1
	s_waitcnt lgkmcnt(0)
	s_barrier
	ds_read2st64_b32 v[48:49], v18 offset1:1
	ds_read2st64_b32 v[52:53], v18 offset0:2 offset1:3
	ds_read2st64_b32 v[50:51], v37 offset0:4 offset1:5
	ds_read2st64_b32 v[54:55], v37 offset0:6 offset1:7
	ds_read2st64_b32 v[56:57], v38 offset0:8 offset1:9
	ds_read2st64_b32 v[58:59], v38 offset0:10 offset1:11
	ds_read2st64_b32 v[60:61], v39 offset0:12 offset1:13
	ds_read2st64_b32 v[62:63], v39 offset0:14 offset1:15
	ds_read2st64_b32 v[64:65], v40 offset0:16 offset1:17
	ds_read2st64_b32 v[66:67], v40 offset0:18 offset1:19
	ds_read2st64_b32 v[68:69], v41 offset0:20 offset1:21
	ds_read2st64_b32 v[70:71], v41 offset0:22 offset1:23
	ds_read2st64_b32 v[72:73], v42 offset0:24 offset1:25
	ds_read2st64_b32 v[74:75], v42 offset0:26 offset1:27
	ds_read2st64_b32 v[80:81], v43 offset0:28 offset1:29
	ds_read2st64_b32 v[82:83], v43 offset0:30 offset1:31
	s_waitcnt lgkmcnt(13)
	v_cvt_pk_bf16_f32 v44, v48, v50
	s_waitcnt lgkmcnt(9)
	v_cvt_pk_bf16_f32 v45, v56, v60
	s_waitcnt lgkmcnt(5)
	v_cvt_pk_bf16_f32 v46, v64, v68
	s_waitcnt lgkmcnt(1)
	v_cvt_pk_bf16_f32 v47, v72, v80
	global_store_dwordx4 v[76:77], v[44:47], off nt
	v_cvt_pk_bf16_f32 v48, v49, v51
	v_cvt_pk_bf16_f32 v49, v57, v61
	v_add_u32_e32 v44, s29, v19
	v_ashrrev_i32_e32 v45, 31, v44
	v_lshlrev_b64 v[44:45], 11, v[44:45]
	v_cvt_pk_bf16_f32 v50, v65, v69
	v_cvt_pk_bf16_f32 v51, v73, v81
	v_lshl_add_u64 v[44:45], v[78:79], 0, v[44:45]
	global_store_dwordx4 v[44:45], v[48:51], off nt
	v_cvt_pk_bf16_f32 v44, v52, v54
	v_cvt_pk_bf16_f32 v45, v58, v62
	v_add_u32_e32 v48, s29, v20
	v_ashrrev_i32_e32 v49, 31, v48
	v_lshlrev_b64 v[48:49], 11, v[48:49]
	v_cvt_pk_bf16_f32 v46, v66, v70
	s_waitcnt lgkmcnt(0)
	v_cvt_pk_bf16_f32 v47, v74, v82
	v_lshl_add_u64 v[48:49], v[78:79], 0, v[48:49]
	global_store_dwordx4 v[48:49], v[44:47], off nt
	v_add_u32_e32 v48, s29, v21
	v_ashrrev_i32_e32 v49, 31, v48
	v_lshlrev_b64 v[48:49], 11, v[48:49]
	v_cvt_pk_bf16_f32 v44, v53, v55
	v_cvt_pk_bf16_f32 v45, v59, v63
	v_cvt_pk_bf16_f32 v46, v67, v71
	v_cvt_pk_bf16_f32 v47, v75, v83
	v_lshl_add_u64 v[48:49], v[78:79], 0, v[48:49]
	global_store_dwordx4 v[48:49], v[44:47], off nt
	s_barrier

.LBB0_53:
	s_andn2_b64 vcc, exec, s[4:5]
	s_cbranch_vccnz .LBB0_42
	s_ashr_i32 s0, s3, 31
	s_lshr_b32 s0, s0, 28
	s_add_i32 s0, s3, s0
	s_ashr_i32 s0, s0, 4
	s_lshl_b32 s4, s0, 6
	s_lshl_b32 s0, s0, 12
	s_sub_i32 s34, s12, s0
	v_add_u32_e32 v74, s4, v16
	s_ashr_i32 s35, s34, 31
	v_lshl_add_u64 v[72:73], s[34:35], 2, v[6:7]
	v_add_u32_e32 v46, 8, v74
	v_add_u32_e32 v52, 16, v74
	v_add_u32_e32 v54, 24, v74
	v_add_u32_e32 v60, 32, v74
	v_add_u32_e32 v62, 40, v74
	v_mad_i64_i32 v[44:45], s[38:39], v74, s28, v[72:73]
	v_mad_i64_i32 v[48:49], s[38:39], v46, s28, v[72:73]
	v_mad_i64_i32 v[52:53], s[38:39], v52, s28, v[72:73]
	v_mad_i64_i32 v[56:57], s[38:39], v54, s28, v[72:73]
	v_mad_i64_i32 v[60:61], s[38:39], v60, s28, v[72:73]
	v_mad_i64_i32 v[64:65], s[38:39], v62, s28, v[72:73]
	global_load_dwordx4 v[44:47], v[44:45], off nt
	s_nop 0
	global_load_dwordx4 v[48:51], v[48:49], off nt
	s_nop 0
	global_load_dwordx4 v[52:55], v[52:53], off nt
	s_nop 0
	global_load_dwordx4 v[56:59], v[56:57], off nt
	s_nop 0
	global_load_dwordx4 v[60:63], v[60:61], off nt
	s_nop 0
	global_load_dwordx4 v[64:67], v[64:65], off nt
	v_add_u32_e32 v68, 48, v74
	v_mad_i64_i32 v[68:69], s[38:39], v68, s28, v[72:73]
	global_load_dwordx4 v[68:71], v[68:69], off nt
	v_add_u32_e32 v74, 56, v74
	v_mad_i64_i32 v[72:73], s[38:39], v74, s28, v[72:73]
	global_load_dwordx4 v[72:75], v[72:73], off nt
	v_add_u32_e32 v78, s34, v17
	s_ashr_i32 s5, s4, 31
	v_ashrrev_i32_e32 v79, 31, v78
	v_add_u32_e32 v80, 64, v78
	v_lshl_add_u64 v[76:77], s[4:5], 1, v[8:9]
	v_lshlrev_b64 v[82:83], 11, v[78:79]
	v_ashrrev_i32_e32 v81, 31, v80
	v_lshl_add_u64 v[82:83], v[76:77], 0, v[82:83]
	v_lshlrev_b64 v[80:81], 11, v[80:81]
	v_lshl_add_u64 v[80:81], v[76:77], 0, v[80:81]
	s_waitcnt vmcnt(7)
	ds_write2_b32 v22, v44, v45 offset1:1
	ds_write2_b32 v22, v46, v47 offset0:2 offset1:3
	s_waitcnt vmcnt(6)
	ds_write2_b32 v23, v48, v49 offset1:1
	ds_write2_b32 v24, v50, v51 offset1:1
	s_waitcnt vmcnt(5)
	ds_write2_b32 v25, v52, v53 offset1:1
	ds_write2_b32 v26, v54, v55 offset1:1
	s_waitcnt vmcnt(4)
	ds_write2_b32 v27, v56, v57 offset1:1
	ds_write2_b32 v28, v58, v59 offset1:1
	s_waitcnt vmcnt(3)
	ds_write2_b32 v29, v60, v61 offset1:1
	ds_write2_b32 v30, v62, v63 offset1:1
	s_waitcnt vmcnt(2)
	ds_write2_b32 v31, v64, v65 offset1:1
	ds_write2_b32 v32, v66, v67 offset1:1
	s_waitcnt vmcnt(1)
	ds_write2_b32 v33, v68, v69 offset1:1
	ds_write2_b32 v34, v70, v71 offset1:1
	s_waitcnt vmcnt(0)
	ds_write2_b32 v35, v72, v73 offset1:1
	ds_write2_b32 v36, v74, v75 offset1:1
	s_waitcnt lgkmcnt(0)
	s_barrier
	ds_read2st64_b32 v[48:49], v18 offset1:1
	ds_read2st64_b32 v[52:53], v18 offset0:2 offset1:3
	ds_read2st64_b32 v[50:51], v37 offset0:4 offset1:5
	ds_read2st64_b32 v[54:55], v37 offset0:6 offset1:7
	ds_read2st64_b32 v[56:57], v38 offset0:8 offset1:9
	ds_read2st64_b32 v[58:59], v38 offset0:10 offset1:11
	ds_read2st64_b32 v[60:61], v39 offset0:12 offset1:13
	ds_read2st64_b32 v[62:63], v39 offset0:14 offset1:15
	ds_read2st64_b32 v[64:65], v40 offset0:16 offset1:17
	ds_read2st64_b32 v[66:67], v40 offset0:18 offset1:19
	ds_read2st64_b32 v[68:69], v41 offset0:20 offset1:21
	ds_read2st64_b32 v[70:71], v41 offset0:22 offset1:23
	ds_read2st64_b32 v[72:73], v42 offset0:24 offset1:25
	ds_read2st64_b32 v[74:75], v42 offset0:26 offset1:27
	ds_read2st64_b32 v[84:85], v43 offset0:28 offset1:29
	ds_read2st64_b32 v[86:87], v43 offset0:30 offset1:31
	s_waitcnt lgkmcnt(13)
	v_cvt_pk_bf16_f32 v44, v48, v50
	s_waitcnt lgkmcnt(9)
	v_cvt_pk_bf16_f32 v45, v56, v60
	s_waitcnt lgkmcnt(5)
	v_cvt_pk_bf16_f32 v46, v64, v68
	s_waitcnt lgkmcnt(1)
	v_cvt_pk_bf16_f32 v47, v72, v84
	v_cvt_pk_bf16_f32 v48, v49, v51
	v_cvt_pk_bf16_f32 v49, v57, v61
	v_cvt_pk_bf16_f32 v50, v65, v69
	v_cvt_pk_bf16_f32 v51, v73, v85
	global_store_dwordx4 v[82:83], v[44:47], off nt
	global_store_dwordx4 v[80:81], v[48:51], off nt
	s_nop 0
	v_cvt_pk_bf16_f32 v44, v52, v54
	v_add_u32_e32 v48, 0x80, v78
	v_ashrrev_i32_e32 v49, 31, v48
	v_lshlrev_b64 v[48:49], 11, v[48:49]
	v_cvt_pk_bf16_f32 v45, v58, v62
	v_cvt_pk_bf16_f32 v46, v66, v70
	s_waitcnt lgkmcnt(0)
	v_cvt_pk_bf16_f32 v47, v74, v86
	v_lshl_add_u64 v[48:49], v[76:77], 0, v[48:49]
	global_store_dwordx4 v[48:49], v[44:47], off nt
	v_add_u32_e32 v48, 0xc0, v78
	v_ashrrev_i32_e32 v49, 31, v48
	v_lshlrev_b64 v[48:49], 11, v[48:49]
	v_cvt_pk_bf16_f32 v44, v53, v55
	v_cvt_pk_bf16_f32 v45, v59, v63
	v_cvt_pk_bf16_f32 v46, v67, v71
	v_cvt_pk_bf16_f32 v47, v75, v87
	v_lshl_add_u64 v[48:49], v[76:77], 0, v[48:49]
	global_store_dwordx4 v[48:49], v[44:47], off nt
	s_barrier
	s_branch .LBB0_42
.LBB0_55:
	s_cmp_eq_u32 s101, 0x340
	s_cbranch_scc1 .Lp4_tr_ret
	s_cmp_gt_i32 s57, 1
	s_cselect_b64 s[0:1], -1, 0
	s_and_b64 s[4:5], s[8:9], s[0:1]
	s_andn2_b64 vcc, exec, s[4:5]
	s_cbranch_vccnz .LBB0_111
	s_waitcnt vmcnt(0)
	s_and_b64 vcc, exec, s[10:11]
	s_waitcnt lgkmcnt(0)
	s_barrier
	s_cbranch_vccnz .LBB0_110
	v_mbcnt_lo_u32_b32 v0, -1, 0
	v_mbcnt_hi_u32_b32 v0, -1, v0
	v_cmp_eq_u32_e32 vcc, 0, v0
	s_and_saveexec_b64 s[4:5], vcc
	s_cbranch_execz .LBB0_109
	s_add_i32 s3, 0, 0x23f00
	v_mov_b32_e32 v0, s3
	s_waitcnt vmcnt(0) expcnt(0) lgkmcnt(0)
	ds_read_b32 v2, v0
	s_add_i32 s3, 0, 0x23f04
	v_mov_b32_e32 v0, s3
	ds_read_b32 v0, v0
	s_waitcnt lgkmcnt(1)
	v_cmp_ne_u32_e32 vcc, 0, v2
	s_cbranch_vccnz .LBB0_73
	s_add_u32 s8, s54, 0x1ec00200
	s_addc_u32 s9, s55, 0
	s_add_u32 s12, s54, 0x1ec00400
	s_addc_u32 s13, s55, 0
	s_add_u32 s22, s54, 0x1ec00500
	s_addc_u32 s23, s55, 0
	s_add_u32 s28, s54, 0x1ec00600
	s_addc_u32 s29, s55, 0
	s_add_u32 s34, s54, 0x1ec00700
	s_addc_u32 s35, s55, 0
	s_add_u32 s38, s54, 0x1ec00800
	s_addc_u32 s39, s55, 0
	s_add_u32 s40, s54, 0x1ec00900
	s_addc_u32 s41, s55, 0
	s_add_u32 s42, s54, 0x1ec00a00
	s_addc_u32 s43, s55, 0
	s_add_u32 s60, s54, 0x1ec00b00
	s_addc_u32 s61, s55, 0
	s_add_u32 s62, s54, 0x1ec00c00
	s_addc_u32 s63, s55, 0
	s_add_u32 s64, s54, 0x1ec00d00
	s_addc_u32 s65, s55, 0
	s_add_u32 s66, s54, 0x1ec00e00
	s_addc_u32 s67, s55, 0
	s_add_u32 s68, s54, 0x1ec00f00
	s_addc_u32 s69, s55, 0
	s_add_u32 s70, s54, 0x1ec01000
	s_addc_u32 s71, s55, 0
	s_add_u32 s72, s54, 0x1ec01100
	s_addc_u32 s73, s55, 0
	s_add_u32 s74, s54, 0x1ec01200
	v_readlane_b32 s3, v240, 0
	s_addc_u32 s75, s55, 0
	s_mul_i32 s3, s59, s3
	s_add_u32 s76, s54, 0x1ec01300
	s_mul_i32 s3, s3, s58
	s_addc_u32 s77, s55, 0
	s_mov_b32 s14, 1
	v_mov_b32_e32 v16, 0
	s_branch .LBB0_61

.Lpf_entry:
	s_cmp_ge_u32 s2, 200
	s_cbranch_scc1 .Lp4_tr
	s_cmp_lg_u32 s95, 0
	s_cbranch_scc1 .LBB0_496
	s_cmp_gt_u32 s2, 199
	s_cbranch_scc1 .LBB0_496
	s_add_i32 s0, s2, -72
	s_lshr_b32 s1, s0, 3
	s_and_b32 s3, s2, 7
	s_and_b32 s6, s1, 7
	s_lshl_b32 s7, s6, 3
	s_or_b32 s3, s3, s7
	s_lshr_b32 s1, s1, 3
	s_cmp_eq_u32 s6, 7
	s_cselect_b32 s7, 2, 2
	s_add_u32 s98, s54, 0x1ec04000
	s_addc_u32 s99, s55, 0
	s_lshl_b32 s8, s3, 8
	s_add_u32 s98, s98, s8
	s_addc_u32 s99, s99, 0
	s_lshr_b32 s8, s3, 1
	s_add_u32 s14, s54, 0x15c00000
	s_addc_u32 s15, s55, 0
	s_mov_b32 s9, 0xe000
	s_mov_b32 s12, 0x380000
	s_bitcmp1_b32 s3, 0
	s_cmov_b32 s9, 0x12000
	s_cmov_b32 s12, 0x480000
	s_cselect_b32 s14, s14, s52
	s_cselect_b32 s15, s15, s53
	s_mul_i32 s13, s12, s8
	s_add_u32 s12, s14, s13
	s_addc_u32 s13, s15, 0
	s_lshr_b32 s16, s9, 6
	s_cmp_eq_u32 s7, 2
	s_cbranch_scc1 .Lpf_nh2
	s_add_i32 s17, s16, 2
	s_mul_i32 s17, s17, 0xaaab
	s_lshr_b32 s17, s17, 17
	s_branch .Lpf_per

.Lpf_done:
	s_waitcnt vmcnt(0)
	s_branch .LBB0_496
.Lp4_tr:
	v_writelane_b32 v240, s4, 6
	v_writelane_b32 v240, s5, 7
	v_writelane_b32 v240, s34, 8
	v_writelane_b32 v240, s35, 9
	v_writelane_b32 v240, s38, 10
	v_writelane_b32 v240, s39, 11
	v_readlane_b32 s0, v240, 4
	v_readlane_b32 s1, v240, 5
	s_nop 4
	s_load_dwordx2 s[22:23], s[0:1], 0x58
	s_load_dwordx2 s[26:27], s[0:1], 0x68
	s_load_dwordx2 s[28:29], s[0:1], 0x70
	s_load_dwordx2 s[46:47], s[0:1], 0x28
	s_waitcnt lgkmcnt(0)
	s_mov_b32 s1, 0
	s_movk_i32 s58, 56
	s_add_i32 s3, s2, 56
	s_movk_i32 s101, 0x340
	v_mbcnt_lo_u32_b32 v128, -1, 0
	v_mbcnt_hi_u32_b32 v128, -1, v128
	s_and_b32 s0, s85, 0xffffffc0
	v_add_u32_e32 v146, s0, v128
	s_branch .Lp0_jobs_entry
.Lp4_tr_ret:
	v_readlane_b32 s4, v240, 6
	v_readlane_b32 s5, v240, 7
	v_readlane_b32 s34, v240, 8
	v_readlane_b32 s35, v240, 9
	v_readlane_b32 s38, v240, 10
	v_readlane_b32 s39, v240, 11
	s_movk_i32 s58, 0x100
	s_movk_i32 s101, 0x100
	s_add_u32 s22, s54, 0x5c00000
	s_addc_u32 s23, s55, 0
	s_nop 3

	.amdhsa_kernel _Z14fwd_megakernel4Args
		.amdhsa_group_segment_fixed_size 0
		.amdhsa_private_segment_fixed_size 0
		.amdhsa_kernarg_size 408
		.amdhsa_user_sgpr_count 2
		.amdhsa_user_sgpr_dispatch_ptr 0
		.amdhsa_user_sgpr_queue_ptr 0
		.amdhsa_user_sgpr_kernarg_segment_ptr 1
		.amdhsa_user_sgpr_dispatch_id 0
		.amdhsa_user_sgpr_kernarg_preload_length 0
		.amdhsa_user_sgpr_kernarg_preload_offset 0
		.amdhsa_user_sgpr_private_segment_size 0
		.amdhsa_uses_dynamic_stack 0
		.amdhsa_enable_private_segment 0
		.amdhsa_system_sgpr_workgroup_id_x 1
		.amdhsa_system_sgpr_workgroup_id_y 0
		.amdhsa_system_sgpr_workgroup_id_z 0
		.amdhsa_system_sgpr_workgroup_info 0
		.amdhsa_system_vgpr_workitem_id 2
		.amdhsa_next_free_vgpr 241
		.amdhsa_next_free_sgpr 102
		.amdhsa_accum_offset 244
		.amdhsa_reserve_vcc 1
		.amdhsa_float_round_mode_32 0
		.amdhsa_float_round_mode_16_64 0
		.amdhsa_float_denorm_mode_32 3
		.amdhsa_float_denorm_mode_16_64 3
		.amdhsa_dx10_clamp 1
		.amdhsa_ieee_mode 1
		.amdhsa_fp16_overflow 0
		.amdhsa_tg_split 0
		.amdhsa_exception_fp_ieee_invalid_op 0
		.amdhsa_exception_fp_denorm_src 0
		.amdhsa_exception_fp_ieee_div_zero 0
		.amdhsa_exception_fp_ieee_overflow 0
		.amdhsa_exception_fp_ieee_underflow 0
		.amdhsa_exception_fp_ieee_inexact 0
		.amdhsa_exception_int_div_zero 0
	.end_amdhsa_kernel

amdhsa.kernels:
  - .agpr_count:     0
    .args:
      - .offset:         0
        .size:           152
        .value_kind:     by_value
      - .offset:         152
        .size:           4
        .value_kind:     hidden_block_count_x
      - .offset:         156
        .size:           4
        .value_kind:     hidden_block_count_y
      - .offset:         160
        .size:           4
        .value_kind:     hidden_block_count_z
      - .offset:         164
        .size:           2
        .value_kind:     hidden_group_size_x
      - .offset:         166
        .size:           2
        .value_kind:     hidden_group_size_y
      - .offset:         168
        .size:           2
        .value_kind:     hidden_group_size_z
      - .offset:         170
        .size:           2
        .value_kind:     hidden_remainder_x
      - .offset:         172
        .size:           2
        .value_kind:     hidden_remainder_y
      - .offset:         174
        .size:           2
        .value_kind:     hidden_remainder_z
      - .offset:         192
        .size:           8
        .value_kind:     hidden_global_offset_x
      - .offset:         200
        .size:           8
        .value_kind:     hidden_global_offset_y
      - .offset:         208
        .size:           8
        .value_kind:     hidden_global_offset_z
      - .offset:         216
        .size:           2
        .value_kind:     hidden_grid_dims
      - .offset:         240
        .size:           8
        .value_kind:     hidden_multigrid_sync_arg
      - .offset:         272
        .size:           4
        .value_kind:     hidden_dynamic_lds_size
    .group_segment_fixed_size: 0
    .kernarg_segment_align: 8
    .kernarg_segment_size: 408
    .language:       OpenCL C
    .language_version:
      - 2
      - 0
    .max_flat_workgroup_size: 512
    .name:           _Z14fwd_megakernel4Args
    .private_segment_fixed_size: 0
    .sgpr_count:     108
    .sgpr_spill_count: 4
    .symbol:         _Z14fwd_megakernel4Args.kd
    .uniform_work_group_size: 1
    .uses_dynamic_stack: false
    .vgpr_count:     241
    .vgpr_spill_count: 0
    .wavefront_size: 64
